# plus A2: deferred-max test on per-lane partial max; cross-half swap, new max and alpha only on the rare path (branch instead of select)
# speedup vs baseline: 1.0102x; 1.0020x over previous
; #define SBAR() __builtin_amdgcn_sched_barrier(0)
; #define RESC2(O, SL, a) do { if (__any((a) < 1.f)) { if (hi == 0) SL[r32] = (a); asm volatile("s_waitcnt lgkmcnt(0)" ::: "memory"); \
;     _Pragma("unroll") for (int d = 0; d < 4; ++d) _Pragma("unroll") for (int r = 0; r < 16; ++r) O[d][r] *= SL[crow(r, hi)]; } } while (0)
; __device__ __forceinline__ void softmax_tile(f32x16& p0, f32x16& p1, float& m, float& l, float& alpha, float cb, bf16x8& pa0, bf16x8& pa1, bf16x8& pa2, bf16x8& pa3) {
;   float mx_[4] = {p0[0], p0[1], p0[2], p0[3]};
; #pragma unroll
;   for (int r = 4; r < 16; ++r) mx_[r & 3] = fmaxf(mx_[r & 3], p0[r]);
; #pragma unroll
;   for (int r = 0; r < 16; ++r) mx_[r & 3] = fmaxf(mx_[r & 3], p1[r]);
;   float pmax = fmaxf(fmaxf(mx_[0], mx_[1]), fmaxf(mx_[2], mx_[3]));
;   { auto rr = __builtin_amdgcn_permlane32_swap(__float_as_uint(pmax), __float_as_uint(pmax), false, false);
;     pmax = fmaxf(__uint_as_float(rr[0]), __uint_as_float(rr[1])); }
;   pmax += cb;
;   float mn;
;   if (__builtin_expect(__all(pmax - m <= THR2), 1)) { mn = m; alpha = 1.f; }
;   else { mn = fmaxf(m, pmax); alpha = __builtin_amdgcn_exp2f(m - mn); m = mn; }
;   const float off = cb - mn;
; #pragma unroll
;   for (int r = 0; r < 16; ++r) p0[r] = __builtin_amdgcn_exp2f(p0[r] + off);
; #pragma unroll
;   for (int r = 0; r < 16; ++r) p1[r] = __builtin_amdgcn_exp2f(p1[r] + off);
;   float sm_[4] = {p0[0], p0[1], p0[2], p0[3]};
; #pragma unroll
;   for (int r = 4; r < 16; ++r) sm_[r & 3] += p0[r];
; #pragma unroll
;   for (int r = 0; r < 16; ++r) sm_[r & 3] += p1[r];
;   float ps = (sm_[0] + sm_[1]) + (sm_[2] + sm_[3]);
;   { auto rr = __builtin_amdgcn_permlane32_swap(__float_as_uint(ps), __float_as_uint(ps), false, false);
;     ps = __uint_as_float(rr[0]) + __uint_as_float(rr[1]); }
;   l = l * alpha + ps;
;     ...
;   PK4(p0, 0, pa0); PK4(p0, 8, pa1); PK4(p1, 0, pa2); PK4(p1, 8, pa3);
;     ...
; }
; __device__ __forceinline__ void attn_unit_A2(const bf16_t* __restrict__ Qb, int ldq, const bf16_t* __restrict__ Kh, int ldk, const bf16_t* __restrict__ Vh, int ldv, int nkeys, int q0, ...
;     ...
;     SBAR();
;     softmax_tile(s0, s1, m0, l0, al0, cb, pa0, pa1, pa2, pa3);
;     RESC2(oa, sl0, al0);
.LBB0_337:
	s_nop 4
	v_cndmask_b32_e64 v2, v197, 0, s[22:23]
	v_cndmask_b32_e64 v227, v207, v2, s[8:9]
	v_max_f32_e32 v2, v160, v164
	v_max_f32_e32 v3, v161, v165
	v_max_f32_e32 v4, v163, v167
	v_max3_f32 v5, v162, v166, v170
	v_max3_f32 v4, v4, v171, v175
	v_max3_f32 v2, v2, v168, v172
	v_max3_f32 v3, v3, v169, v173
	v_max3_f32 v5, v5, v174, v146
	v_max3_f32 v4, v4, v147, v151
	v_max3_f32 v2, v2, v144, v148
	v_max3_f32 v3, v3, v145, v149
	v_max3_f32 v5, v5, v150, v154
	v_max3_f32 v4, v4, v155, v159
	v_max3_f32 v2, v2, v152, v156
	v_max3_f32 v3, v3, v153, v157
	v_max3_f32 v4, v5, v158, v4
	v_max3_f32 v2, v2, v3, v4
	v_add_f32_e32 v3, v227, v2
	v_sub_f32_e32 v3, v3, v0
	v_cmp_ge_f32_e32 vcc, s48, v3
	s_cmp_eq_u64 vcc, exec
	s_cbranch_scc0 .Lmy_A_rare0
	v_sub_f32_e32 v2, v227, v0
	v_mov_b32_e32 v15, 1.0
.Lmy_A_back0:
	v_add_f32_e32 v3, v160, v2
	v_add_f32_e32 v4, v161, v2
	v_add_f32_e32 v5, v162, v2
	v_add_f32_e32 v6, v163, v2
	v_add_f32_e32 v7, v164, v2
	v_add_f32_e32 v8, v165, v2
	v_add_f32_e32 v9, v166, v2
	v_add_f32_e32 v10, v167, v2
	v_exp_f32_e32 v3, v3
	v_exp_f32_e32 v4, v4
	v_exp_f32_e32 v5, v5
	v_exp_f32_e32 v6, v6
	v_exp_f32_e32 v7, v7
	v_exp_f32_e32 v8, v8
	v_exp_f32_e32 v9, v9
	v_exp_f32_e32 v10, v10
	v_add_f32_e32 v11, v168, v2
	v_add_f32_e32 v12, v169, v2
	v_add_f32_e32 v13, v170, v2
	v_add_f32_e32 v160, v171, v2
	v_exp_f32_e32 v11, v11
	v_exp_f32_e32 v12, v12
	v_exp_f32_e32 v13, v13
	v_exp_f32_e32 v160, v160
	v_add_f32_e32 v161, v172, v2
	v_add_f32_e32 v162, v173, v2
	v_add_f32_e32 v163, v174, v2
	v_add_f32_e32 v164, v175, v2
	v_exp_f32_e32 v161, v161
	v_exp_f32_e32 v162, v162
	v_exp_f32_e32 v163, v163
	v_exp_f32_e32 v164, v164
	v_add_f32_e32 v144, v144, v2
	v_add_f32_e32 v145, v145, v2
	v_add_f32_e32 v146, v146, v2
	v_add_f32_e32 v147, v147, v2
	v_exp_f32_e32 v144, v144
	v_exp_f32_e32 v145, v145
	v_exp_f32_e32 v146, v146
	v_exp_f32_e32 v147, v147
	v_add_f32_e32 v148, v148, v2
	v_add_f32_e32 v149, v149, v2
	v_add_f32_e32 v150, v150, v2
	v_add_f32_e32 v151, v151, v2
	v_add_f32_e32 v152, v152, v2
	v_add_f32_e32 v153, v153, v2
	v_add_f32_e32 v154, v154, v2
	v_add_f32_e32 v155, v155, v2
	v_add_f32_e32 v156, v156, v2
	v_add_f32_e32 v157, v157, v2
	v_add_f32_e32 v158, v158, v2
	v_add_f32_e32 v2, v159, v2
	v_exp_f32_e32 v148, v148
	v_exp_f32_e32 v149, v149
	v_exp_f32_e32 v150, v150
	v_exp_f32_e32 v151, v151
	v_exp_f32_e32 v159, v2
	v_add_f32_e32 v2, v7, v3
	v_add_f32_e32 v165, v8, v4
	v_add_f32_e32 v166, v9, v5
	v_add_f32_e32 v167, v10, v6
	v_exp_f32_e32 v152, v152
	v_exp_f32_e32 v153, v153
	v_exp_f32_e32 v154, v154
	v_exp_f32_e32 v155, v155
	v_add_f32_e32 v2, v11, v2
	v_add_f32_e32 v165, v12, v165
	v_add_f32_e32 v166, v13, v166
	v_add_f32_e32 v167, v160, v167
	v_exp_f32_e32 v156, v156
	v_exp_f32_e32 v157, v157
	v_exp_f32_e32 v158, v158
	v_add_f32_e32 v2, v161, v2
	v_add_f32_e32 v165, v162, v165
	v_add_f32_e32 v166, v163, v166
	v_add_f32_e32 v167, v164, v167
	v_add_f32_e32 v2, v144, v2
	v_add_f32_e32 v165, v145, v165
	v_add_f32_e32 v166, v146, v166
	v_add_f32_e32 v167, v147, v167
	v_add_f32_e32 v2, v148, v2
	v_add_f32_e32 v165, v149, v165
	v_add_f32_e32 v166, v150, v166
	v_add_f32_e32 v167, v151, v167
	v_add_f32_e32 v2, v152, v2
	v_add_f32_e32 v165, v153, v165
	v_add_f32_e32 v166, v154, v166
	v_add_f32_e32 v167, v155, v167
	v_add_f32_e32 v2, v156, v2
	v_add_f32_e32 v165, v157, v165
	v_add_f32_e32 v166, v158, v166
	v_add_f32_e32 v167, v159, v167
	v_add_f32_e32 v2, v2, v165
	v_add_f32_e32 v165, v166, v167
	v_add_f32_e32 v220, v2, v165
	v_mov_b32_e32 v221, v220
	v_cvt_pk_bf16_f32 v2, v3, v4
	v_cvt_pk_bf16_f32 v3, v5, v6
	v_cvt_pk_bf16_f32 v4, v7, v8
	v_cvt_pk_bf16_f32 v5, v9, v10
	v_cvt_pk_bf16_f32 v6, v11, v12
	v_cvt_pk_bf16_f32 v7, v13, v160
	v_cvt_pk_bf16_f32 v8, v161, v162
	v_cvt_pk_bf16_f32 v9, v163, v164
	v_cvt_pk_bf16_f32 v10, v144, v145
	v_cvt_pk_bf16_f32 v11, v146, v147
	v_cvt_pk_bf16_f32 v12, v148, v149
	v_cvt_pk_bf16_f32 v13, v150, v151
	v_cvt_pk_bf16_f32 v144, v152, v153
	v_cvt_pk_bf16_f32 v145, v154, v155
	v_cvt_pk_bf16_f32 v146, v156, v157
	v_cvt_pk_bf16_f32 v147, v158, v159
	s_nop 1
	v_permlane32_swap_b32_e32 v220, v221
	v_cmp_gt_f32_e32 vcc, 1.0, v15
	s_cbranch_vccz .LBB0_341
	s_and_saveexec_b64 s[8:9], s[4:5]
	ds_write_b32 v215, v15
	s_or_b64 exec, exec, s[8:9]
	s_waitcnt lgkmcnt(0)
	ds_read_b128 v[148:151], v216 offset:96
	ds_read_b128 v[152:155], v216 offset:64
	ds_read_b128 v[156:159], v216 offset:32
	ds_read_b128 v[160:163], v216
	s_waitcnt lgkmcnt(3)
	v_pk_mul_f32 v[142:143], v[142:143], v[150:151]
	s_waitcnt lgkmcnt(2)
	v_pk_mul_f32 v[138:139], v[138:139], v[154:155]
	s_waitcnt lgkmcnt(1)
	v_pk_mul_f32 v[134:135], v[134:135], v[158:159]
	s_waitcnt lgkmcnt(0)
	v_pk_mul_f32 v[130:131], v[130:131], v[162:163]
	v_pk_mul_f32 v[140:141], v[140:141], v[148:149]
	v_pk_mul_f32 v[136:137], v[136:137], v[152:153]
	v_pk_mul_f32 v[132:133], v[132:133], v[156:157]
	v_pk_mul_f32 v[128:129], v[128:129], v[160:161]
	v_pk_mul_f32 v[110:111], v[110:111], v[150:151]
	v_pk_mul_f32 v[106:107], v[106:107], v[154:155]
	v_pk_mul_f32 v[102:103], v[102:103], v[158:159]
	v_pk_mul_f32 v[98:99], v[98:99], v[162:163]
	v_pk_mul_f32 v[108:109], v[108:109], v[148:149]
	v_pk_mul_f32 v[104:105], v[104:105], v[152:153]
	v_pk_mul_f32 v[100:101], v[100:101], v[156:157]
	v_pk_mul_f32 v[96:97], v[96:97], v[160:161]
	v_pk_mul_f32 v[62:63], v[62:63], v[150:151]
	v_pk_mul_f32 v[58:59], v[58:59], v[154:155]
	v_pk_mul_f32 v[54:55], v[54:55], v[158:159]
	v_pk_mul_f32 v[50:51], v[50:51], v[162:163]
	v_pk_mul_f32 v[60:61], v[60:61], v[148:149]
	v_pk_mul_f32 v[56:57], v[56:57], v[152:153]
	v_pk_mul_f32 v[52:53], v[52:53], v[156:157]
	v_pk_mul_f32 v[48:49], v[48:49], v[160:161]
	v_pk_mul_f32 v[94:95], v[94:95], v[150:151]
	v_pk_mul_f32 v[90:91], v[90:91], v[154:155]
	v_pk_mul_f32 v[86:87], v[86:87], v[158:159]
	v_pk_mul_f32 v[82:83], v[82:83], v[162:163]
	v_pk_mul_f32 v[92:93], v[92:93], v[148:149]
	v_pk_mul_f32 v[88:89], v[88:89], v[152:153]
	v_pk_mul_f32 v[84:85], v[84:85], v[156:157]
	v_pk_mul_f32 v[80:81], v[80:81], v[160:161]

; #define SBAR() __builtin_amdgcn_sched_barrier(0)
; #define RESC2(O, SL, a) do { if (__any((a) < 1.f)) { if (hi == 0) SL[r32] = (a); asm volatile("s_waitcnt lgkmcnt(0)" ::: "memory"); \
;     _Pragma("unroll") for (int d = 0; d < 4; ++d) _Pragma("unroll") for (int r = 0; r < 16; ++r) O[d][r] *= SL[crow(r, hi)]; } } while (0)
; __device__ __forceinline__ void softmax_tile(f32x16& p0, f32x16& p1, float& m, float& l, float& alpha, float cb, bf16x8& pa0, bf16x8& pa1, bf16x8& pa2, bf16x8& pa3) {
;   float mx_[4] = {p0[0], p0[1], p0[2], p0[3]};
; #pragma unroll
;   for (int r = 4; r < 16; ++r) mx_[r & 3] = fmaxf(mx_[r & 3], p0[r]);
; #pragma unroll
;   for (int r = 0; r < 16; ++r) mx_[r & 3] = fmaxf(mx_[r & 3], p1[r]);
;   float pmax = fmaxf(fmaxf(mx_[0], mx_[1]), fmaxf(mx_[2], mx_[3]));
;   { auto rr = __builtin_amdgcn_permlane32_swap(__float_as_uint(pmax), __float_as_uint(pmax), false, false);
;     pmax = fmaxf(__uint_as_float(rr[0]), __uint_as_float(rr[1])); }
;   pmax += cb;
;   float mn;
;   if (__builtin_expect(__all(pmax - m <= THR2), 1)) { mn = m; alpha = 1.f; }
;   else { mn = fmaxf(m, pmax); alpha = __builtin_amdgcn_exp2f(m - mn); m = mn; }
;   const float off = cb - mn;
; #pragma unroll
;   for (int r = 0; r < 16; ++r) p0[r] = __builtin_amdgcn_exp2f(p0[r] + off);
; #pragma unroll
;   for (int r = 0; r < 16; ++r) p1[r] = __builtin_amdgcn_exp2f(p1[r] + off);
;   float sm_[4] = {p0[0], p0[1], p0[2], p0[3]};
; #pragma unroll
;   for (int r = 4; r < 16; ++r) sm_[r & 3] += p0[r];
; #pragma unroll
;   for (int r = 0; r < 16; ++r) sm_[r & 3] += p1[r];
;   float ps = (sm_[0] + sm_[1]) + (sm_[2] + sm_[3]);
;   { auto rr = __builtin_amdgcn_permlane32_swap(__float_as_uint(ps), __float_as_uint(ps), false, false);
;     ps = __uint_as_float(rr[0]) + __uint_as_float(rr[1]); }
;   l = l * alpha + ps;
;     ...
;   PK4(p0, 0, pa0); PK4(p0, 8, pa1); PK4(p1, 0, pa2); PK4(p1, 8, pa3);
;     ...
; }
; __device__ __forceinline__ void attn_unit_A2(const bf16_t* __restrict__ Qb, int ldq, const bf16_t* __restrict__ Kh, int ldk, const bf16_t* __restrict__ Vh, int ldv, int nkeys, int q0, ...
;     ...
;     SBAR();
;     softmax_tile(s0, s1, m1, l1, al1, cb, pa0, pa1, pa2, pa3);
;     RESC2(ob, sl1, al1);
.LBB0_343:
	s_nop 8
	v_max_f32_e32 v2, v160, v164
	v_max_f32_e32 v3, v161, v165
	v_max_f32_e32 v4, v163, v167
	v_max3_f32 v5, v162, v166, v170
	v_max3_f32 v4, v4, v171, v175
	v_max3_f32 v2, v2, v168, v172
	v_max3_f32 v3, v3, v169, v173
	v_max3_f32 v5, v5, v174, v146
	v_max3_f32 v4, v4, v147, v151
	v_max3_f32 v2, v2, v144, v148
	v_max3_f32 v3, v3, v145, v149
	v_max3_f32 v5, v5, v150, v154
	v_max3_f32 v4, v4, v155, v159
	v_max3_f32 v2, v2, v152, v156
	v_max3_f32 v3, v3, v153, v157
	v_max3_f32 v4, v5, v158, v4
	v_max3_f32 v2, v2, v3, v4
	v_add_f32_e32 v3, v227, v2
	v_sub_f32_e32 v3, v3, v218
	v_cmp_ge_f32_e32 vcc, s48, v3
	s_cmp_eq_u64 vcc, exec
	s_cbranch_scc0 .Lmy_A_rare1
	v_sub_f32_e32 v2, v227, v218
	v_mov_b32_e32 v223, 1.0
.Lmy_A_back1:
	v_add_f32_e32 v148, v148, v2
	v_add_f32_e32 v8, v165, v2
	v_exp_f32_e32 v165, v148
	v_add_f32_e32 v148, v149, v2
	v_add_f32_e32 v9, v166, v2
	v_exp_f32_e32 v166, v148
	v_add_f32_e32 v148, v150, v2
	v_exp_f32_e32 v150, v148
	v_add_f32_e32 v148, v151, v2
	v_exp_f32_e32 v151, v148
	v_add_f32_e32 v148, v152, v2
	v_exp_f32_e32 v152, v148
	v_add_f32_e32 v148, v153, v2
	v_add_f32_e32 v3, v160, v2
	v_add_f32_e32 v4, v161, v2
	v_add_f32_e32 v5, v162, v2
	v_add_f32_e32 v6, v163, v2
	v_add_f32_e32 v7, v164, v2
	v_add_f32_e32 v10, v167, v2
	v_exp_f32_e32 v153, v148
	v_add_f32_e32 v148, v154, v2
	v_exp_f32_e32 v3, v3
	v_exp_f32_e32 v4, v4
	v_exp_f32_e32 v5, v5
	v_exp_f32_e32 v6, v6
	v_exp_f32_e32 v7, v7
	v_exp_f32_e32 v8, v8
	v_exp_f32_e32 v9, v9
	v_exp_f32_e32 v10, v10
	v_add_f32_e32 v11, v168, v2
	v_add_f32_e32 v12, v169, v2
	v_add_f32_e32 v13, v170, v2
	v_add_f32_e32 v160, v171, v2
	v_exp_f32_e32 v154, v148
	v_add_f32_e32 v148, v155, v2
	v_exp_f32_e32 v11, v11
	v_exp_f32_e32 v12, v12
	v_exp_f32_e32 v13, v13
	v_exp_f32_e32 v160, v160
	v_add_f32_e32 v161, v172, v2
	v_add_f32_e32 v162, v173, v2
	v_add_f32_e32 v163, v174, v2
	v_add_f32_e32 v164, v175, v2
	v_exp_f32_e32 v155, v148
	v_add_f32_e32 v148, v156, v2
	v_exp_f32_e32 v161, v161
	v_exp_f32_e32 v162, v162
	v_exp_f32_e32 v163, v163
	v_exp_f32_e32 v164, v164
	v_add_f32_e32 v144, v144, v2
	v_add_f32_e32 v145, v145, v2
	v_add_f32_e32 v146, v146, v2
	v_add_f32_e32 v147, v147, v2
	v_exp_f32_e32 v156, v148
	v_add_f32_e32 v148, v157, v2
	v_exp_f32_e32 v144, v144
	v_exp_f32_e32 v145, v145
	v_exp_f32_e32 v146, v146
	v_exp_f32_e32 v147, v147
	v_exp_f32_e32 v157, v148
	v_add_f32_e32 v148, v158, v2
	v_add_f32_e32 v2, v159, v2
	v_exp_f32_e32 v158, v148
	v_exp_f32_e32 v159, v2
	v_add_f32_e32 v2, v7, v3
	v_add_f32_e32 v148, v8, v4
	v_add_f32_e32 v149, v9, v5
	v_add_f32_e32 v167, v10, v6
	v_add_f32_e32 v2, v11, v2
	v_add_f32_e32 v148, v12, v148
	v_add_f32_e32 v149, v13, v149
	v_add_f32_e32 v167, v160, v167
	v_add_f32_e32 v2, v161, v2
	v_add_f32_e32 v148, v162, v148
	v_add_f32_e32 v149, v163, v149
	v_add_f32_e32 v167, v164, v167
	v_add_f32_e32 v2, v144, v2
	v_add_f32_e32 v148, v145, v148
	v_add_f32_e32 v149, v146, v149
	v_add_f32_e32 v167, v147, v167
	v_add_f32_e32 v2, v165, v2
	v_add_f32_e32 v148, v166, v148
	v_add_f32_e32 v149, v150, v149
	v_add_f32_e32 v167, v151, v167
	v_add_f32_e32 v2, v152, v2
	v_add_f32_e32 v148, v153, v148
	v_add_f32_e32 v149, v154, v149
	v_add_f32_e32 v167, v155, v167
	v_add_f32_e32 v2, v156, v2
	v_add_f32_e32 v148, v157, v148
	v_add_f32_e32 v149, v158, v149
	v_add_f32_e32 v167, v159, v167
	v_add_f32_e32 v2, v2, v148
	v_add_f32_e32 v148, v149, v167
	v_add_f32_e32 v148, v2, v148
	v_mov_b32_e32 v149, v148
	v_cvt_pk_bf16_f32 v2, v3, v4
	v_cvt_pk_bf16_f32 v3, v5, v6
	v_cvt_pk_bf16_f32 v4, v7, v8
	v_cvt_pk_bf16_f32 v5, v9, v10
	v_cvt_pk_bf16_f32 v6, v11, v12
	v_cvt_pk_bf16_f32 v7, v13, v160
	v_cvt_pk_bf16_f32 v8, v161, v162
	v_cvt_pk_bf16_f32 v9, v163, v164
	v_cvt_pk_bf16_f32 v10, v144, v145
	v_cvt_pk_bf16_f32 v11, v146, v147
	v_cvt_pk_bf16_f32 v12, v165, v166
	v_cvt_pk_bf16_f32 v13, v150, v151
	v_cvt_pk_bf16_f32 v144, v152, v153
	v_cvt_pk_bf16_f32 v145, v154, v155
	v_cvt_pk_bf16_f32 v146, v156, v157
	v_cvt_pk_bf16_f32 v147, v158, v159
	s_nop 1
	v_permlane32_swap_b32_e32 v148, v149
	v_cmp_gt_f32_e32 vcc, 1.0, v223
	s_cbranch_vccz .LBB0_347
	s_and_saveexec_b64 s[6:7], s[4:5]
	ds_write_b32 v215, v223 offset:128
	s_or_b64 exec, exec, s[6:7]
	s_waitcnt lgkmcnt(0)
	ds_read_b128 v[150:153], v216 offset:224
	ds_read_b128 v[154:157], v216 offset:192
	ds_read_b128 v[158:161], v216 offset:160
	ds_read_b128 v[162:165], v216 offset:128
	s_waitcnt lgkmcnt(3)
	v_pk_mul_f32 v[126:127], v[126:127], v[152:153]
	s_waitcnt lgkmcnt(2)
	v_pk_mul_f32 v[122:123], v[122:123], v[156:157]
	s_waitcnt lgkmcnt(1)
	v_pk_mul_f32 v[118:119], v[118:119], v[160:161]
	s_waitcnt lgkmcnt(0)
	v_pk_mul_f32 v[114:115], v[114:115], v[164:165]
	v_pk_mul_f32 v[124:125], v[124:125], v[150:151]
	v_pk_mul_f32 v[120:121], v[120:121], v[154:155]
	v_pk_mul_f32 v[116:117], v[116:117], v[158:159]
	v_pk_mul_f32 v[112:113], v[112:113], v[162:163]
	v_pk_mul_f32 v[78:79], v[78:79], v[152:153]
	v_pk_mul_f32 v[74:75], v[74:75], v[156:157]
	v_pk_mul_f32 v[70:71], v[70:71], v[160:161]
	v_pk_mul_f32 v[66:67], v[66:67], v[164:165]
	v_pk_mul_f32 v[76:77], v[76:77], v[150:151]
	v_pk_mul_f32 v[72:73], v[72:73], v[154:155]
	v_pk_mul_f32 v[68:69], v[68:69], v[158:159]
	v_pk_mul_f32 v[64:65], v[64:65], v[162:163]
	v_pk_mul_f32 v[30:31], v[30:31], v[152:153]
	v_pk_mul_f32 v[26:27], v[26:27], v[156:157]
	v_pk_mul_f32 v[22:23], v[22:23], v[160:161]
	v_pk_mul_f32 v[18:19], v[18:19], v[164:165]
	v_pk_mul_f32 v[28:29], v[28:29], v[150:151]
	v_pk_mul_f32 v[24:25], v[24:25], v[154:155]
	v_pk_mul_f32 v[20:21], v[20:21], v[158:159]
	v_pk_mul_f32 v[16:17], v[16:17], v[162:163]
	v_pk_mul_f32 v[46:47], v[46:47], v[152:153]
	v_pk_mul_f32 v[42:43], v[42:43], v[156:157]
	v_pk_mul_f32 v[38:39], v[38:39], v[160:161]
	v_pk_mul_f32 v[34:35], v[34:35], v[164:165]
	v_pk_mul_f32 v[44:45], v[44:45], v[150:151]
	v_pk_mul_f32 v[40:41], v[40:41], v[154:155]
	v_pk_mul_f32 v[36:37], v[36:37], v[158:159]
	v_pk_mul_f32 v[32:33], v[32:33], v[162:163]

; __device__ __forceinline__ void softmax_tile(f32x16& p0, f32x16& p1, float& m, float& l, float& alpha, float cb, bf16x8& pa0, bf16x8& pa1, bf16x8& pa2, bf16x8& pa3) {
;     ...
;   float pmax = fmaxf(fmaxf(mx_[0], mx_[1]), fmaxf(mx_[2], mx_[3]));
;   { auto rr = __builtin_amdgcn_permlane32_swap(__float_as_uint(pmax), __float_as_uint(pmax), false, false);
;     pmax = fmaxf(__uint_as_float(rr[0]), __uint_as_float(rr[1])); }
;   pmax += cb;
;   float mn;
;   if (__builtin_expect(__all(pmax - m <= THR2), 1)) { mn = m; alpha = 1.f; }
;   else { mn = fmaxf(m, pmax); alpha = __builtin_amdgcn_exp2f(m - mn); m = mn; }
.Lmy_A_rare0:
	v_mov_b32_e32 v3, v2
	s_nop 1
	v_permlane32_swap_b32_e32 v2, v3
	v_max_f32_e32 v2, v2, v3
	v_add_f32_e32 v2, v227, v2
	v_max_f32_e32 v2, v0, v2
	v_sub_f32_e32 v3, v0, v2
	v_exp_f32_e32 v3, v3
	v_mov_b32_e32 v0, v2
	v_sub_f32_e32 v2, v227, v0
	v_mov_b32_e32 v15, v3
	s_branch .Lmy_A_back0
.Lmy_A_rare1:
	v_mov_b32_e32 v3, v2
	s_nop 1
	v_permlane32_swap_b32_e32 v2, v3
	v_max_f32_e32 v2, v2, v3
	v_add_f32_e32 v2, v227, v2
	v_max_f32_e32 v2, v218, v2
	v_sub_f32_e32 v3, v218, v2
	v_exp_f32_e32 v3, v3
	v_mov_b32_e32 v218, v2
	v_sub_f32_e32 v2, v227, v218
	v_mov_b32_e32 v223, v3
	s_branch .Lmy_A_back1
